# baseline (speedup 1.0000x reference)
.LBB0_552:
	s_and_saveexec_b64 s[2:3], s[8:9]
	s_cbranch_execz .LBB0_554
	v_mov_b64_e32 v[0:1], s[0:1]
	flat_atomic_add v0, v[0:1], v243 sc0
	v_mov_b32_e32 v1, s33
	s_waitcnt vmcnt(0) lgkmcnt(0)
	ds_write_b32 v1, v0
